# DN scan inner loops rewritten by hand: 57 instr/step (was 75), operand loads one step ahead with immediate LDS offsets, running store pointer
# speedup vs baseline: 1.0072x; 1.0072x over previous
.LBB0_906:
	v_mov_b32_e32 v136, v94
	v_mov_b32_e32 v137, v95
	v_mov_b32_e32 v138, 0
	s_lshl_b32 s100, s24, 9
	s_ashr_i32 s101, s100, 31
.Ldnscan_906:
	s_waitcnt lgkmcnt(0)
	v_pk_fma_f32 v[106:107], v[74:75], v[2:3], 0 op_sel_hi:[1,1,0]
	v_pk_fma_f32 v[108:109], v[74:75], v[30:31], 0 op_sel_hi:[1,1,0]
	ds_read_b128 v[66:69], v136 offset:800
	v_pk_fma_f32 v[106:107], v[78:79], v[4:5], v[106:107]
	v_pk_fma_f32 v[108:109], v[78:79], v[32:33], v[108:109]
	ds_read_b128 v[62:65], v136 offset:816
	v_pk_fma_f32 v[106:107], v[80:81], v[6:7], v[106:107]
	v_pk_fma_f32 v[108:109], v[80:81], v[26:27], v[108:109]
	ds_read_b128 v[58:61], v136 offset:832
	v_pk_fma_f32 v[106:107], v[82:83], v[8:9], v[106:107]
	v_pk_fma_f32 v[108:109], v[82:83], v[28:29], v[108:109]
	ds_read_b128 v[54:57], v136 offset:848
	v_pk_fma_f32 v[106:107], v[84:85], v[14:15], v[106:107]
	v_pk_fma_f32 v[108:109], v[84:85], v[22:23], v[108:109]
	ds_read_b128 v[50:53], v136 offset:1056
	v_pk_fma_f32 v[106:107], v[86:87], v[16:17], v[106:107]
	v_pk_fma_f32 v[108:109], v[86:87], v[24:25], v[108:109]
	ds_read_b128 v[46:49], v136 offset:1072
	v_pk_fma_f32 v[106:107], v[88:89], v[10:11], v[106:107]
	v_pk_fma_f32 v[108:109], v[88:89], v[18:19], v[108:109]
	ds_read_b128 v[42:45], v136 offset:1088
	v_pk_fma_f32 v[106:107], v[90:91], v[12:13], v[106:107]
	v_pk_fma_f32 v[108:109], v[90:91], v[20:21], v[108:109]
	ds_read_b128 v[38:41], v136 offset:1104
	v_add_f32_e32 v130, v106, v107
	v_add_f32_e32 v131, v108, v109
	v_pk_mul_f32 v[114:115], v[34:35], v[74:75] op_sel_hi:[0,1]
	v_add_f32_dpp v130, v130, v130 quad_perm:[1,0,3,2] row_mask:0xf bank_mask:0xf bound_ctrl:1
	v_add_f32_dpp v131, v131, v131 quad_perm:[1,0,3,2] row_mask:0xf bank_mask:0xf bound_ctrl:1
	v_pk_mul_f32 v[116:117], v[34:35], v[78:79] op_sel_hi:[0,1]
	v_add_f32_dpp v130, v130, v130 quad_perm:[2,3,0,1] row_mask:0xf bank_mask:0xf bound_ctrl:1
	v_add_f32_dpp v131, v131, v131 quad_perm:[2,3,0,1] row_mask:0xf bank_mask:0xf bound_ctrl:1
	ds_read_b32 v0, v137 offset:1312
	v_fma_f32 v130, -v34, v130, v73
	ds_read_b96 v[70:72], v138 offset:1568
	v_mul_f32_e32 v130, v35, v130
	v_mul_f32_e32 v131, v34, v131
	v_pk_mul_f32 v[118:119], v[34:35], v[80:81] op_sel_hi:[0,1]
	v_fma_f32 v131, v36, v130, v131
	v_pk_mul_f32 v[120:121], v[34:35], v[82:83] op_sel_hi:[0,1]
	v_bfe_u32 v132, v131, 16, 1
	v_pk_mul_f32 v[122:123], v[34:35], v[84:85] op_sel_hi:[0,1]
	v_add3_u32 v132, v131, v132, s28
	global_store_short_d16_hi v[92:93], v132, off
	v_pk_mul_f32 v[124:125], v[34:35], v[86:87] op_sel_hi:[0,1]
	v_lshl_add_u64 v[92:93], v[92:93], 0, s[100:101]
	v_pk_mul_f32 v[126:127], v[34:35], v[88:89] op_sel_hi:[0,1]
	v_pk_mul_f32 v[128:129], v[34:35], v[90:91] op_sel_hi:[0,1]
	v_pk_fma_f32 v[74:75], v[2:3], v[130:131], v[114:115] op_sel_hi:[1,0,1]
	v_pk_fma_f32 v[78:79], v[4:5], v[130:131], v[116:117] op_sel_hi:[1,0,1]
	v_pk_fma_f32 v[80:81], v[6:7], v[130:131], v[118:119] op_sel_hi:[1,0,1]
	v_pk_fma_f32 v[82:83], v[8:9], v[130:131], v[120:121] op_sel_hi:[1,0,1]
	v_pk_fma_f32 v[84:85], v[14:15], v[130:131], v[122:123] op_sel_hi:[1,0,1]
	v_pk_fma_f32 v[86:87], v[16:17], v[130:131], v[124:125] op_sel_hi:[1,0,1]
	v_pk_fma_f32 v[88:89], v[10:11], v[130:131], v[126:127] op_sel_hi:[1,0,1]
	v_pk_fma_f32 v[90:91], v[12:13], v[130:131], v[128:129] op_sel_hi:[1,0,1]
	s_waitcnt lgkmcnt(0)
	v_pk_fma_f32 v[110:111], v[74:75], v[50:51], 0 op_sel_hi:[1,1,0]
	v_pk_fma_f32 v[112:113], v[74:75], v[66:67], 0 op_sel_hi:[1,1,0]
	ds_read_b128 v[30:33], v136 offset:1600
	v_pk_fma_f32 v[110:111], v[78:79], v[52:53], v[110:111]
	v_pk_fma_f32 v[112:113], v[78:79], v[68:69], v[112:113]
	ds_read_b128 v[26:29], v136 offset:1616
	v_pk_fma_f32 v[110:111], v[80:81], v[46:47], v[110:111]
	v_pk_fma_f32 v[112:113], v[80:81], v[62:63], v[112:113]
	ds_read_b128 v[22:25], v136 offset:1632
	v_pk_fma_f32 v[110:111], v[82:83], v[48:49], v[110:111]
	v_pk_fma_f32 v[112:113], v[82:83], v[64:65], v[112:113]
	ds_read_b128 v[18:21], v136 offset:1648
	v_pk_fma_f32 v[110:111], v[84:85], v[42:43], v[110:111]
	v_pk_fma_f32 v[112:113], v[84:85], v[58:59], v[112:113]
	ds_read_b128 v[2:5], v136 offset:1856
	v_pk_fma_f32 v[110:111], v[86:87], v[44:45], v[110:111]
	v_pk_fma_f32 v[112:113], v[86:87], v[60:61], v[112:113]
	ds_read_b128 v[6:9], v136 offset:1872
	v_pk_fma_f32 v[110:111], v[88:89], v[38:39], v[110:111]
	v_pk_fma_f32 v[112:113], v[88:89], v[54:55], v[112:113]
	ds_read_b128 v[14:17], v136 offset:1888
	v_pk_fma_f32 v[110:111], v[90:91], v[40:41], v[110:111]
	v_pk_fma_f32 v[112:113], v[90:91], v[56:57], v[112:113]
	ds_read_b128 v[10:13], v136 offset:1904
	v_add_f32_e32 v134, v110, v111
	v_add_f32_e32 v135, v112, v113
	v_pk_mul_f32 v[114:115], v[70:71], v[74:75] op_sel_hi:[0,1]
	v_add_f32_dpp v134, v134, v134 quad_perm:[1,0,3,2] row_mask:0xf bank_mask:0xf bound_ctrl:1
	v_add_f32_dpp v135, v135, v135 quad_perm:[1,0,3,2] row_mask:0xf bank_mask:0xf bound_ctrl:1
	v_pk_mul_f32 v[116:117], v[70:71], v[78:79] op_sel_hi:[0,1]
	v_add_f32_dpp v134, v134, v134 quad_perm:[2,3,0,1] row_mask:0xf bank_mask:0xf bound_ctrl:1
	v_add_f32_dpp v135, v135, v135 quad_perm:[2,3,0,1] row_mask:0xf bank_mask:0xf bound_ctrl:1
	ds_read_b32 v73, v137 offset:2112
	v_fma_f32 v134, -v70, v134, v0
	ds_read_b96 v[34:36], v138 offset:2368
	v_mul_f32_e32 v134, v71, v134
	v_mul_f32_e32 v135, v70, v135
	v_pk_mul_f32 v[118:119], v[70:71], v[80:81] op_sel_hi:[0,1]
	v_fma_f32 v135, v72, v134, v135
	v_pk_mul_f32 v[120:121], v[70:71], v[82:83] op_sel_hi:[0,1]
	v_bfe_u32 v133, v135, 16, 1
	v_pk_mul_f32 v[122:123], v[70:71], v[84:85] op_sel_hi:[0,1]
	v_add3_u32 v133, v135, v133, s28
	global_store_short_d16_hi v[92:93], v133, off
	v_pk_mul_f32 v[124:125], v[70:71], v[86:87] op_sel_hi:[0,1]
	v_lshl_add_u64 v[92:93], v[92:93], 0, s[100:101]
	v_pk_mul_f32 v[126:127], v[70:71], v[88:89] op_sel_hi:[0,1]
	v_pk_mul_f32 v[128:129], v[70:71], v[90:91] op_sel_hi:[0,1]
	v_pk_fma_f32 v[74:75], v[50:51], v[134:135], v[114:115] op_sel_hi:[1,0,1]
	v_pk_fma_f32 v[78:79], v[52:53], v[134:135], v[116:117] op_sel_hi:[1,0,1]
	v_pk_fma_f32 v[80:81], v[46:47], v[134:135], v[118:119] op_sel_hi:[1,0,1]
	v_pk_fma_f32 v[82:83], v[48:49], v[134:135], v[120:121] op_sel_hi:[1,0,1]
	v_pk_fma_f32 v[84:85], v[42:43], v[134:135], v[122:123] op_sel_hi:[1,0,1]
	v_pk_fma_f32 v[86:87], v[44:45], v[134:135], v[124:125] op_sel_hi:[1,0,1]
	v_pk_fma_f32 v[88:89], v[38:39], v[134:135], v[126:127] op_sel_hi:[1,0,1]
	v_pk_fma_f32 v[90:91], v[40:41], v[134:135], v[128:129] op_sel_hi:[1,0,1]
	s_waitcnt lgkmcnt(0)
	v_pk_fma_f32 v[106:107], v[74:75], v[2:3], 0 op_sel_hi:[1,1,0]
	v_pk_fma_f32 v[108:109], v[74:75], v[30:31], 0 op_sel_hi:[1,1,0]
	ds_read_b128 v[66:69], v136 offset:2400
	v_pk_fma_f32 v[106:107], v[78:79], v[4:5], v[106:107]
	v_pk_fma_f32 v[108:109], v[78:79], v[32:33], v[108:109]
	ds_read_b128 v[62:65], v136 offset:2416
	v_pk_fma_f32 v[106:107], v[80:81], v[6:7], v[106:107]
	v_pk_fma_f32 v[108:109], v[80:81], v[26:27], v[108:109]
	ds_read_b128 v[58:61], v136 offset:2432
	v_pk_fma_f32 v[106:107], v[82:83], v[8:9], v[106:107]
	v_pk_fma_f32 v[108:109], v[82:83], v[28:29], v[108:109]
	ds_read_b128 v[54:57], v136 offset:2448
	v_pk_fma_f32 v[106:107], v[84:85], v[14:15], v[106:107]
	v_pk_fma_f32 v[108:109], v[84:85], v[22:23], v[108:109]
	ds_read_b128 v[50:53], v136 offset:2656
	v_pk_fma_f32 v[106:107], v[86:87], v[16:17], v[106:107]
	v_pk_fma_f32 v[108:109], v[86:87], v[24:25], v[108:109]
	ds_read_b128 v[46:49], v136 offset:2672
	v_pk_fma_f32 v[106:107], v[88:89], v[10:11], v[106:107]
	v_pk_fma_f32 v[108:109], v[88:89], v[18:19], v[108:109]
	ds_read_b128 v[42:45], v136 offset:2688
	v_pk_fma_f32 v[106:107], v[90:91], v[12:13], v[106:107]
	v_pk_fma_f32 v[108:109], v[90:91], v[20:21], v[108:109]
	ds_read_b128 v[38:41], v136 offset:2704
	v_add_f32_e32 v130, v106, v107
	v_add_f32_e32 v131, v108, v109
	v_pk_mul_f32 v[114:115], v[34:35], v[74:75] op_sel_hi:[0,1]
	v_add_f32_dpp v130, v130, v130 quad_perm:[1,0,3,2] row_mask:0xf bank_mask:0xf bound_ctrl:1
	v_add_f32_dpp v131, v131, v131 quad_perm:[1,0,3,2] row_mask:0xf bank_mask:0xf bound_ctrl:1
	v_pk_mul_f32 v[116:117], v[34:35], v[78:79] op_sel_hi:[0,1]
	v_add_f32_dpp v130, v130, v130 quad_perm:[2,3,0,1] row_mask:0xf bank_mask:0xf bound_ctrl:1
	v_add_f32_dpp v131, v131, v131 quad_perm:[2,3,0,1] row_mask:0xf bank_mask:0xf bound_ctrl:1
	ds_read_b32 v0, v137 offset:2912
	v_fma_f32 v130, -v34, v130, v73
	ds_read_b96 v[70:72], v138 offset:3168
	v_mul_f32_e32 v130, v35, v130
	v_mul_f32_e32 v131, v34, v131
	v_pk_mul_f32 v[118:119], v[34:35], v[80:81] op_sel_hi:[0,1]
	v_fma_f32 v131, v36, v130, v131
	v_pk_mul_f32 v[120:121], v[34:35], v[82:83] op_sel_hi:[0,1]
	v_bfe_u32 v132, v131, 16, 1
	v_pk_mul_f32 v[122:123], v[34:35], v[84:85] op_sel_hi:[0,1]
	v_add3_u32 v132, v131, v132, s28
	global_store_short_d16_hi v[92:93], v132, off
	v_pk_mul_f32 v[124:125], v[34:35], v[86:87] op_sel_hi:[0,1]
	v_lshl_add_u64 v[92:93], v[92:93], 0, s[100:101]
	v_pk_mul_f32 v[126:127], v[34:35], v[88:89] op_sel_hi:[0,1]
	v_pk_mul_f32 v[128:129], v[34:35], v[90:91] op_sel_hi:[0,1]
	v_pk_fma_f32 v[74:75], v[2:3], v[130:131], v[114:115] op_sel_hi:[1,0,1]
	v_pk_fma_f32 v[78:79], v[4:5], v[130:131], v[116:117] op_sel_hi:[1,0,1]
	v_pk_fma_f32 v[80:81], v[6:7], v[130:131], v[118:119] op_sel_hi:[1,0,1]
	v_pk_fma_f32 v[82:83], v[8:9], v[130:131], v[120:121] op_sel_hi:[1,0,1]
	v_pk_fma_f32 v[84:85], v[14:15], v[130:131], v[122:123] op_sel_hi:[1,0,1]
	v_pk_fma_f32 v[86:87], v[16:17], v[130:131], v[124:125] op_sel_hi:[1,0,1]
	v_pk_fma_f32 v[88:89], v[10:11], v[130:131], v[126:127] op_sel_hi:[1,0,1]
	v_pk_fma_f32 v[90:91], v[12:13], v[130:131], v[128:129] op_sel_hi:[1,0,1]
	s_waitcnt lgkmcnt(0)
	v_pk_fma_f32 v[110:111], v[74:75], v[50:51], 0 op_sel_hi:[1,1,0]
	v_pk_fma_f32 v[112:113], v[74:75], v[66:67], 0 op_sel_hi:[1,1,0]
	ds_read_b128 v[30:33], v136 offset:3200
	v_pk_fma_f32 v[110:111], v[78:79], v[52:53], v[110:111]
	v_pk_fma_f32 v[112:113], v[78:79], v[68:69], v[112:113]
	ds_read_b128 v[26:29], v136 offset:3216
	v_pk_fma_f32 v[110:111], v[80:81], v[46:47], v[110:111]
	v_pk_fma_f32 v[112:113], v[80:81], v[62:63], v[112:113]
	ds_read_b128 v[22:25], v136 offset:3232
	v_pk_fma_f32 v[110:111], v[82:83], v[48:49], v[110:111]
	v_pk_fma_f32 v[112:113], v[82:83], v[64:65], v[112:113]
	ds_read_b128 v[18:21], v136 offset:3248
	v_pk_fma_f32 v[110:111], v[84:85], v[42:43], v[110:111]
	v_pk_fma_f32 v[112:113], v[84:85], v[58:59], v[112:113]
	ds_read_b128 v[2:5], v136 offset:3456
	v_pk_fma_f32 v[110:111], v[86:87], v[44:45], v[110:111]
	v_pk_fma_f32 v[112:113], v[86:87], v[60:61], v[112:113]
	ds_read_b128 v[6:9], v136 offset:3472
	v_pk_fma_f32 v[110:111], v[88:89], v[38:39], v[110:111]
	v_pk_fma_f32 v[112:113], v[88:89], v[54:55], v[112:113]
	ds_read_b128 v[14:17], v136 offset:3488
	v_pk_fma_f32 v[110:111], v[90:91], v[40:41], v[110:111]
	v_pk_fma_f32 v[112:113], v[90:91], v[56:57], v[112:113]
	ds_read_b128 v[10:13], v136 offset:3504
	v_add_f32_e32 v134, v110, v111
	v_add_f32_e32 v135, v112, v113
	v_pk_mul_f32 v[114:115], v[70:71], v[74:75] op_sel_hi:[0,1]
	v_add_f32_dpp v134, v134, v134 quad_perm:[1,0,3,2] row_mask:0xf bank_mask:0xf bound_ctrl:1
	v_add_f32_dpp v135, v135, v135 quad_perm:[1,0,3,2] row_mask:0xf bank_mask:0xf bound_ctrl:1
	v_pk_mul_f32 v[116:117], v[70:71], v[78:79] op_sel_hi:[0,1]
	v_add_f32_dpp v134, v134, v134 quad_perm:[2,3,0,1] row_mask:0xf bank_mask:0xf bound_ctrl:1
	v_add_f32_dpp v135, v135, v135 quad_perm:[2,3,0,1] row_mask:0xf bank_mask:0xf bound_ctrl:1
	ds_read_b32 v73, v137 offset:3712
	v_fma_f32 v134, -v70, v134, v0
	ds_read_b96 v[34:36], v138 offset:3968
	v_mul_f32_e32 v134, v71, v134
	v_mul_f32_e32 v135, v70, v135
	v_pk_mul_f32 v[118:119], v[70:71], v[80:81] op_sel_hi:[0,1]
	v_fma_f32 v135, v72, v134, v135
	v_pk_mul_f32 v[120:121], v[70:71], v[82:83] op_sel_hi:[0,1]
	v_bfe_u32 v133, v135, 16, 1
	v_pk_mul_f32 v[122:123], v[70:71], v[84:85] op_sel_hi:[0,1]
	v_add3_u32 v133, v135, v133, s28
	global_store_short_d16_hi v[92:93], v133, off
	v_pk_mul_f32 v[124:125], v[70:71], v[86:87] op_sel_hi:[0,1]
	v_lshl_add_u64 v[92:93], v[92:93], 0, s[100:101]
	v_pk_mul_f32 v[126:127], v[70:71], v[88:89] op_sel_hi:[0,1]
	v_pk_mul_f32 v[128:129], v[70:71], v[90:91] op_sel_hi:[0,1]
	v_pk_fma_f32 v[74:75], v[50:51], v[134:135], v[114:115] op_sel_hi:[1,0,1]
	v_pk_fma_f32 v[78:79], v[52:53], v[134:135], v[116:117] op_sel_hi:[1,0,1]
	v_pk_fma_f32 v[80:81], v[46:47], v[134:135], v[118:119] op_sel_hi:[1,0,1]
	v_pk_fma_f32 v[82:83], v[48:49], v[134:135], v[120:121] op_sel_hi:[1,0,1]
	v_pk_fma_f32 v[84:85], v[42:43], v[134:135], v[122:123] op_sel_hi:[1,0,1]
	v_pk_fma_f32 v[86:87], v[44:45], v[134:135], v[124:125] op_sel_hi:[1,0,1]
	v_pk_fma_f32 v[88:89], v[38:39], v[134:135], v[126:127] op_sel_hi:[1,0,1]
	v_pk_fma_f32 v[90:91], v[40:41], v[134:135], v[128:129] op_sel_hi:[1,0,1]
	v_add_u32_e32 v136, 0xc80, v136
	v_add_u32_e32 v137, 0xc80, v137
	v_add_u32_e32 v138, 0xc80, v138
	s_add_i32 s10, s10, 4
	s_cmp_lt_i32 s10, 14
	s_cbranch_scc1 .Ldnscan_906

.LBB0_916:
	v_add_u32_e32 v136, 0x3200, v94
	v_add_u32_e32 v137, 0x3200, v95
	v_mov_b32_e32 v138, 0x3200
	s_lshl_b32 s100, s24, 9
	s_ashr_i32 s101, s100, 31
.Ldnscan_916:
	s_waitcnt lgkmcnt(0)
	v_pk_fma_f32 v[106:107], v[74:75], v[2:3], 0 op_sel_hi:[1,1,0]
	v_pk_fma_f32 v[108:109], v[74:75], v[30:31], 0 op_sel_hi:[1,1,0]
	ds_read_b128 v[66:69], v136 offset:800
	v_pk_fma_f32 v[106:107], v[78:79], v[4:5], v[106:107]
	v_pk_fma_f32 v[108:109], v[78:79], v[32:33], v[108:109]
	ds_read_b128 v[62:65], v136 offset:816
	v_pk_fma_f32 v[106:107], v[80:81], v[6:7], v[106:107]
	v_pk_fma_f32 v[108:109], v[80:81], v[26:27], v[108:109]
	ds_read_b128 v[58:61], v136 offset:832
	v_pk_fma_f32 v[106:107], v[82:83], v[8:9], v[106:107]
	v_pk_fma_f32 v[108:109], v[82:83], v[28:29], v[108:109]
	ds_read_b128 v[54:57], v136 offset:848
	v_pk_fma_f32 v[106:107], v[84:85], v[14:15], v[106:107]
	v_pk_fma_f32 v[108:109], v[84:85], v[22:23], v[108:109]
	ds_read_b128 v[50:53], v136 offset:1056
	v_pk_fma_f32 v[106:107], v[86:87], v[16:17], v[106:107]
	v_pk_fma_f32 v[108:109], v[86:87], v[24:25], v[108:109]
	ds_read_b128 v[46:49], v136 offset:1072
	v_pk_fma_f32 v[106:107], v[88:89], v[10:11], v[106:107]
	v_pk_fma_f32 v[108:109], v[88:89], v[18:19], v[108:109]
	ds_read_b128 v[42:45], v136 offset:1088
	v_pk_fma_f32 v[106:107], v[90:91], v[12:13], v[106:107]
	v_pk_fma_f32 v[108:109], v[90:91], v[20:21], v[108:109]
	ds_read_b128 v[38:41], v136 offset:1104
	v_add_f32_e32 v130, v106, v107
	v_add_f32_e32 v131, v108, v109
	v_pk_mul_f32 v[114:115], v[34:35], v[74:75] op_sel_hi:[0,1]
	v_add_f32_dpp v130, v130, v130 quad_perm:[1,0,3,2] row_mask:0xf bank_mask:0xf bound_ctrl:1
	v_add_f32_dpp v131, v131, v131 quad_perm:[1,0,3,2] row_mask:0xf bank_mask:0xf bound_ctrl:1
	v_pk_mul_f32 v[116:117], v[34:35], v[78:79] op_sel_hi:[0,1]
	v_add_f32_dpp v130, v130, v130 quad_perm:[2,3,0,1] row_mask:0xf bank_mask:0xf bound_ctrl:1
	v_add_f32_dpp v131, v131, v131 quad_perm:[2,3,0,1] row_mask:0xf bank_mask:0xf bound_ctrl:1
	ds_read_b32 v0, v137 offset:1312
	v_fma_f32 v130, -v34, v130, v73
	ds_read_b96 v[70:72], v138 offset:1568
	v_mul_f32_e32 v130, v35, v130
	v_mul_f32_e32 v131, v34, v131
	v_pk_mul_f32 v[118:119], v[34:35], v[80:81] op_sel_hi:[0,1]
	v_fma_f32 v131, v36, v130, v131
	v_pk_mul_f32 v[120:121], v[34:35], v[82:83] op_sel_hi:[0,1]
	v_bfe_u32 v132, v131, 16, 1
	v_pk_mul_f32 v[122:123], v[34:35], v[84:85] op_sel_hi:[0,1]
	v_add3_u32 v132, v131, v132, s28
	global_store_short_d16_hi v[92:93], v132, off
	v_pk_mul_f32 v[124:125], v[34:35], v[86:87] op_sel_hi:[0,1]
	v_lshl_add_u64 v[92:93], v[92:93], 0, s[100:101]
	v_pk_mul_f32 v[126:127], v[34:35], v[88:89] op_sel_hi:[0,1]
	v_pk_mul_f32 v[128:129], v[34:35], v[90:91] op_sel_hi:[0,1]
	v_pk_fma_f32 v[74:75], v[2:3], v[130:131], v[114:115] op_sel_hi:[1,0,1]
	v_pk_fma_f32 v[78:79], v[4:5], v[130:131], v[116:117] op_sel_hi:[1,0,1]
	v_pk_fma_f32 v[80:81], v[6:7], v[130:131], v[118:119] op_sel_hi:[1,0,1]
	v_pk_fma_f32 v[82:83], v[8:9], v[130:131], v[120:121] op_sel_hi:[1,0,1]
	v_pk_fma_f32 v[84:85], v[14:15], v[130:131], v[122:123] op_sel_hi:[1,0,1]
	v_pk_fma_f32 v[86:87], v[16:17], v[130:131], v[124:125] op_sel_hi:[1,0,1]
	v_pk_fma_f32 v[88:89], v[10:11], v[130:131], v[126:127] op_sel_hi:[1,0,1]
	v_pk_fma_f32 v[90:91], v[12:13], v[130:131], v[128:129] op_sel_hi:[1,0,1]
	s_waitcnt lgkmcnt(0)
	v_pk_fma_f32 v[110:111], v[74:75], v[50:51], 0 op_sel_hi:[1,1,0]
	v_pk_fma_f32 v[112:113], v[74:75], v[66:67], 0 op_sel_hi:[1,1,0]
	ds_read_b128 v[30:33], v136 offset:1600
	v_pk_fma_f32 v[110:111], v[78:79], v[52:53], v[110:111]
	v_pk_fma_f32 v[112:113], v[78:79], v[68:69], v[112:113]
	ds_read_b128 v[26:29], v136 offset:1616
	v_pk_fma_f32 v[110:111], v[80:81], v[46:47], v[110:111]
	v_pk_fma_f32 v[112:113], v[80:81], v[62:63], v[112:113]
	ds_read_b128 v[22:25], v136 offset:1632
	v_pk_fma_f32 v[110:111], v[82:83], v[48:49], v[110:111]
	v_pk_fma_f32 v[112:113], v[82:83], v[64:65], v[112:113]
	ds_read_b128 v[18:21], v136 offset:1648
	v_pk_fma_f32 v[110:111], v[84:85], v[42:43], v[110:111]
	v_pk_fma_f32 v[112:113], v[84:85], v[58:59], v[112:113]
	ds_read_b128 v[2:5], v136 offset:1856
	v_pk_fma_f32 v[110:111], v[86:87], v[44:45], v[110:111]
	v_pk_fma_f32 v[112:113], v[86:87], v[60:61], v[112:113]
	ds_read_b128 v[6:9], v136 offset:1872
	v_pk_fma_f32 v[110:111], v[88:89], v[38:39], v[110:111]
	v_pk_fma_f32 v[112:113], v[88:89], v[54:55], v[112:113]
	ds_read_b128 v[14:17], v136 offset:1888
	v_pk_fma_f32 v[110:111], v[90:91], v[40:41], v[110:111]
	v_pk_fma_f32 v[112:113], v[90:91], v[56:57], v[112:113]
	ds_read_b128 v[10:13], v136 offset:1904
	v_add_f32_e32 v134, v110, v111
	v_add_f32_e32 v135, v112, v113
	v_pk_mul_f32 v[114:115], v[70:71], v[74:75] op_sel_hi:[0,1]
	v_add_f32_dpp v134, v134, v134 quad_perm:[1,0,3,2] row_mask:0xf bank_mask:0xf bound_ctrl:1
	v_add_f32_dpp v135, v135, v135 quad_perm:[1,0,3,2] row_mask:0xf bank_mask:0xf bound_ctrl:1
	v_pk_mul_f32 v[116:117], v[70:71], v[78:79] op_sel_hi:[0,1]
	v_add_f32_dpp v134, v134, v134 quad_perm:[2,3,0,1] row_mask:0xf bank_mask:0xf bound_ctrl:1
	v_add_f32_dpp v135, v135, v135 quad_perm:[2,3,0,1] row_mask:0xf bank_mask:0xf bound_ctrl:1
	ds_read_b32 v73, v137 offset:2112
	v_fma_f32 v134, -v70, v134, v0
	ds_read_b96 v[34:36], v138 offset:2368
	v_mul_f32_e32 v134, v71, v134
	v_mul_f32_e32 v135, v70, v135
	v_pk_mul_f32 v[118:119], v[70:71], v[80:81] op_sel_hi:[0,1]
	v_fma_f32 v135, v72, v134, v135
	v_pk_mul_f32 v[120:121], v[70:71], v[82:83] op_sel_hi:[0,1]
	v_bfe_u32 v133, v135, 16, 1
	v_pk_mul_f32 v[122:123], v[70:71], v[84:85] op_sel_hi:[0,1]
	v_add3_u32 v133, v135, v133, s28
	global_store_short_d16_hi v[92:93], v133, off
	v_pk_mul_f32 v[124:125], v[70:71], v[86:87] op_sel_hi:[0,1]
	v_lshl_add_u64 v[92:93], v[92:93], 0, s[100:101]
	v_pk_mul_f32 v[126:127], v[70:71], v[88:89] op_sel_hi:[0,1]
	v_pk_mul_f32 v[128:129], v[70:71], v[90:91] op_sel_hi:[0,1]
	v_pk_fma_f32 v[74:75], v[50:51], v[134:135], v[114:115] op_sel_hi:[1,0,1]
	v_pk_fma_f32 v[78:79], v[52:53], v[134:135], v[116:117] op_sel_hi:[1,0,1]
	v_pk_fma_f32 v[80:81], v[46:47], v[134:135], v[118:119] op_sel_hi:[1,0,1]
	v_pk_fma_f32 v[82:83], v[48:49], v[134:135], v[120:121] op_sel_hi:[1,0,1]
	v_pk_fma_f32 v[84:85], v[42:43], v[134:135], v[122:123] op_sel_hi:[1,0,1]
	v_pk_fma_f32 v[86:87], v[44:45], v[134:135], v[124:125] op_sel_hi:[1,0,1]
	v_pk_fma_f32 v[88:89], v[38:39], v[134:135], v[126:127] op_sel_hi:[1,0,1]
	v_pk_fma_f32 v[90:91], v[40:41], v[134:135], v[128:129] op_sel_hi:[1,0,1]
	s_waitcnt lgkmcnt(0)
	v_pk_fma_f32 v[106:107], v[74:75], v[2:3], 0 op_sel_hi:[1,1,0]
	v_pk_fma_f32 v[108:109], v[74:75], v[30:31], 0 op_sel_hi:[1,1,0]
	ds_read_b128 v[66:69], v136 offset:2400
	v_pk_fma_f32 v[106:107], v[78:79], v[4:5], v[106:107]
	v_pk_fma_f32 v[108:109], v[78:79], v[32:33], v[108:109]
	ds_read_b128 v[62:65], v136 offset:2416
	v_pk_fma_f32 v[106:107], v[80:81], v[6:7], v[106:107]
	v_pk_fma_f32 v[108:109], v[80:81], v[26:27], v[108:109]
	ds_read_b128 v[58:61], v136 offset:2432
	v_pk_fma_f32 v[106:107], v[82:83], v[8:9], v[106:107]
	v_pk_fma_f32 v[108:109], v[82:83], v[28:29], v[108:109]
	ds_read_b128 v[54:57], v136 offset:2448
	v_pk_fma_f32 v[106:107], v[84:85], v[14:15], v[106:107]
	v_pk_fma_f32 v[108:109], v[84:85], v[22:23], v[108:109]
	ds_read_b128 v[50:53], v136 offset:2656
	v_pk_fma_f32 v[106:107], v[86:87], v[16:17], v[106:107]
	v_pk_fma_f32 v[108:109], v[86:87], v[24:25], v[108:109]
	ds_read_b128 v[46:49], v136 offset:2672
	v_pk_fma_f32 v[106:107], v[88:89], v[10:11], v[106:107]
	v_pk_fma_f32 v[108:109], v[88:89], v[18:19], v[108:109]
	ds_read_b128 v[42:45], v136 offset:2688
	v_pk_fma_f32 v[106:107], v[90:91], v[12:13], v[106:107]
	v_pk_fma_f32 v[108:109], v[90:91], v[20:21], v[108:109]
	ds_read_b128 v[38:41], v136 offset:2704
	v_add_f32_e32 v130, v106, v107
	v_add_f32_e32 v131, v108, v109
	v_pk_mul_f32 v[114:115], v[34:35], v[74:75] op_sel_hi:[0,1]
	v_add_f32_dpp v130, v130, v130 quad_perm:[1,0,3,2] row_mask:0xf bank_mask:0xf bound_ctrl:1
	v_add_f32_dpp v131, v131, v131 quad_perm:[1,0,3,2] row_mask:0xf bank_mask:0xf bound_ctrl:1
	v_pk_mul_f32 v[116:117], v[34:35], v[78:79] op_sel_hi:[0,1]
	v_add_f32_dpp v130, v130, v130 quad_perm:[2,3,0,1] row_mask:0xf bank_mask:0xf bound_ctrl:1
	v_add_f32_dpp v131, v131, v131 quad_perm:[2,3,0,1] row_mask:0xf bank_mask:0xf bound_ctrl:1
	ds_read_b32 v0, v137 offset:2912
	v_fma_f32 v130, -v34, v130, v73
	ds_read_b96 v[70:72], v138 offset:3168
	v_mul_f32_e32 v130, v35, v130
	v_mul_f32_e32 v131, v34, v131
	v_pk_mul_f32 v[118:119], v[34:35], v[80:81] op_sel_hi:[0,1]
	v_fma_f32 v131, v36, v130, v131
	v_pk_mul_f32 v[120:121], v[34:35], v[82:83] op_sel_hi:[0,1]
	v_bfe_u32 v132, v131, 16, 1
	v_pk_mul_f32 v[122:123], v[34:35], v[84:85] op_sel_hi:[0,1]
	v_add3_u32 v132, v131, v132, s28
	global_store_short_d16_hi v[92:93], v132, off
	v_pk_mul_f32 v[124:125], v[34:35], v[86:87] op_sel_hi:[0,1]
	v_lshl_add_u64 v[92:93], v[92:93], 0, s[100:101]
	v_pk_mul_f32 v[126:127], v[34:35], v[88:89] op_sel_hi:[0,1]
	v_pk_mul_f32 v[128:129], v[34:35], v[90:91] op_sel_hi:[0,1]
	v_pk_fma_f32 v[74:75], v[2:3], v[130:131], v[114:115] op_sel_hi:[1,0,1]
	v_pk_fma_f32 v[78:79], v[4:5], v[130:131], v[116:117] op_sel_hi:[1,0,1]
	v_pk_fma_f32 v[80:81], v[6:7], v[130:131], v[118:119] op_sel_hi:[1,0,1]
	v_pk_fma_f32 v[82:83], v[8:9], v[130:131], v[120:121] op_sel_hi:[1,0,1]
	v_pk_fma_f32 v[84:85], v[14:15], v[130:131], v[122:123] op_sel_hi:[1,0,1]
	v_pk_fma_f32 v[86:87], v[16:17], v[130:131], v[124:125] op_sel_hi:[1,0,1]
	v_pk_fma_f32 v[88:89], v[10:11], v[130:131], v[126:127] op_sel_hi:[1,0,1]
	v_pk_fma_f32 v[90:91], v[12:13], v[130:131], v[128:129] op_sel_hi:[1,0,1]
	s_waitcnt lgkmcnt(0)
	v_pk_fma_f32 v[110:111], v[74:75], v[50:51], 0 op_sel_hi:[1,1,0]
	v_pk_fma_f32 v[112:113], v[74:75], v[66:67], 0 op_sel_hi:[1,1,0]
	ds_read_b128 v[30:33], v136 offset:3200
	v_pk_fma_f32 v[110:111], v[78:79], v[52:53], v[110:111]
	v_pk_fma_f32 v[112:113], v[78:79], v[68:69], v[112:113]
	ds_read_b128 v[26:29], v136 offset:3216
	v_pk_fma_f32 v[110:111], v[80:81], v[46:47], v[110:111]
	v_pk_fma_f32 v[112:113], v[80:81], v[62:63], v[112:113]
	ds_read_b128 v[22:25], v136 offset:3232
	v_pk_fma_f32 v[110:111], v[82:83], v[48:49], v[110:111]
	v_pk_fma_f32 v[112:113], v[82:83], v[64:65], v[112:113]
	ds_read_b128 v[18:21], v136 offset:3248
	v_pk_fma_f32 v[110:111], v[84:85], v[42:43], v[110:111]
	v_pk_fma_f32 v[112:113], v[84:85], v[58:59], v[112:113]
	ds_read_b128 v[2:5], v136 offset:3456
	v_pk_fma_f32 v[110:111], v[86:87], v[44:45], v[110:111]
	v_pk_fma_f32 v[112:113], v[86:87], v[60:61], v[112:113]
	ds_read_b128 v[6:9], v136 offset:3472
	v_pk_fma_f32 v[110:111], v[88:89], v[38:39], v[110:111]
	v_pk_fma_f32 v[112:113], v[88:89], v[54:55], v[112:113]
	ds_read_b128 v[14:17], v136 offset:3488
	v_pk_fma_f32 v[110:111], v[90:91], v[40:41], v[110:111]
	v_pk_fma_f32 v[112:113], v[90:91], v[56:57], v[112:113]
	ds_read_b128 v[10:13], v136 offset:3504
	v_add_f32_e32 v134, v110, v111
	v_add_f32_e32 v135, v112, v113
	v_pk_mul_f32 v[114:115], v[70:71], v[74:75] op_sel_hi:[0,1]
	v_add_f32_dpp v134, v134, v134 quad_perm:[1,0,3,2] row_mask:0xf bank_mask:0xf bound_ctrl:1
	v_add_f32_dpp v135, v135, v135 quad_perm:[1,0,3,2] row_mask:0xf bank_mask:0xf bound_ctrl:1
	v_pk_mul_f32 v[116:117], v[70:71], v[78:79] op_sel_hi:[0,1]
	v_add_f32_dpp v134, v134, v134 quad_perm:[2,3,0,1] row_mask:0xf bank_mask:0xf bound_ctrl:1
	v_add_f32_dpp v135, v135, v135 quad_perm:[2,3,0,1] row_mask:0xf bank_mask:0xf bound_ctrl:1
	ds_read_b32 v73, v137 offset:3712
	v_fma_f32 v134, -v70, v134, v0
	ds_read_b96 v[34:36], v138 offset:3968
	v_mul_f32_e32 v134, v71, v134
	v_mul_f32_e32 v135, v70, v135
	v_pk_mul_f32 v[118:119], v[70:71], v[80:81] op_sel_hi:[0,1]
	v_fma_f32 v135, v72, v134, v135
	v_pk_mul_f32 v[120:121], v[70:71], v[82:83] op_sel_hi:[0,1]
	v_bfe_u32 v133, v135, 16, 1
	v_pk_mul_f32 v[122:123], v[70:71], v[84:85] op_sel_hi:[0,1]
	v_add3_u32 v133, v135, v133, s28
	global_store_short_d16_hi v[92:93], v133, off
	v_pk_mul_f32 v[124:125], v[70:71], v[86:87] op_sel_hi:[0,1]
	v_lshl_add_u64 v[92:93], v[92:93], 0, s[100:101]
	v_pk_mul_f32 v[126:127], v[70:71], v[88:89] op_sel_hi:[0,1]
	v_pk_mul_f32 v[128:129], v[70:71], v[90:91] op_sel_hi:[0,1]
	v_pk_fma_f32 v[74:75], v[50:51], v[134:135], v[114:115] op_sel_hi:[1,0,1]
	v_pk_fma_f32 v[78:79], v[52:53], v[134:135], v[116:117] op_sel_hi:[1,0,1]
	v_pk_fma_f32 v[80:81], v[46:47], v[134:135], v[118:119] op_sel_hi:[1,0,1]
	v_pk_fma_f32 v[82:83], v[48:49], v[134:135], v[120:121] op_sel_hi:[1,0,1]
	v_pk_fma_f32 v[84:85], v[42:43], v[134:135], v[122:123] op_sel_hi:[1,0,1]
	v_pk_fma_f32 v[86:87], v[44:45], v[134:135], v[124:125] op_sel_hi:[1,0,1]
	v_pk_fma_f32 v[88:89], v[38:39], v[134:135], v[126:127] op_sel_hi:[1,0,1]
	v_pk_fma_f32 v[90:91], v[40:41], v[134:135], v[128:129] op_sel_hi:[1,0,1]
	v_add_u32_e32 v136, 0xc80, v136
	v_add_u32_e32 v137, 0xc80, v137
	v_add_u32_e32 v138, 0xc80, v138
	s_add_i32 s6, s6, 4
	s_cmp_lt_i32 s6, 14
	s_cbranch_scc1 .Ldnscan_916
	s_branch .LBB0_899
